# v27: v26 + P12 conv-state copy loop: iterations 2 and 3 issued together (two loads in flight)
# baseline (speedup 1.0000x reference)
; __device__ __forceinline__ float bf2f(unsigned b) { return __uint_as_float(b << 16); }
; __global__ void __launch_bounds__(512, 2) mega_fwd(Args args) {
;     ...
;         for (int idx = gt; idx < 2 * FF + 32 * 2 * FF; idx += NGT) {
;             if (idx < 2 * FF) { const int j = idx / FF, f = idx % FF; out[O_PSC + idx] = LASTG[((size_t)63 * 2 + j) * FF + f]; }
;             else { const int q = idx - 2 * FF, b = q / (2 * FF), j = (q / FF) & 1, f = q % FF; out[O_SSC + q] = bf2f(GB[(size_t)(T + b * 4 + 2 + j) * FF + f]); }
;         }
.LBB0_843:
	s_or_b64 exec, exec, s[8:9]
	v_add_u32_e32 v194, s40, v194
	v_add_u32_e32 v12, s40, v194
	s_load_dwordx4 s[20:23], s[28:29], 0xf0
	v_mov_b32_e32 v1, 0
	v_add_u32_e32 v0, 0xffffd400, v194
	v_mul_hi_u32 v4, v0, s11
	v_lshrrev_b32_e32 v2, 12, v4
	v_bfe_u32 v5, v4, 12, 1
	v_lshrrev_b32_e32 v4, 11, v4
	v_mul_u32_u24_e32 v2, 0x1600, v2
	v_and_or_b32 v4, v4, s12, v5
	v_sub_u32_e32 v0, v0, v2
	s_waitcnt lgkmcnt(0)
	v_mov_b32_e32 v2, s22
	v_mov_b32_e32 v3, s23
	v_add_u32_e32 v4, 0x4002, v4
	v_mad_u64_u32 v[2:3], s[16:17], v4, s13, v[2:3]
	v_lshl_add_u64 v[2:3], v[0:1], 1, v[2:3]
	v_add_co_u32_e32 v2, vcc, 0x15d00000, v2
	s_nop 1
	v_addc_co_u32_e32 v3, vcc, 0, v3, vcc
	global_load_ushort v0, v[2:3], off
	v_cmp_ge_i32_e32 vcc, s15, v12
	s_and_saveexec_b64 s[8:9], vcc
	v_add_u32_e32 v6, 0xffffd400, v12
	v_mul_hi_u32 v10, v6, s11
	v_lshrrev_b32_e32 v8, 12, v10
	v_bfe_u32 v11, v10, 12, 1
	v_lshrrev_b32_e32 v10, 11, v10
	v_mul_u32_u24_e32 v8, 0x1600, v8
	v_and_or_b32 v10, v10, s12, v11
	v_sub_u32_e32 v6, v6, v8
	v_mov_b32_e32 v7, 0
	v_mov_b32_e32 v8, s22
	v_mov_b32_e32 v9, s23
	v_add_u32_e32 v10, 0x4002, v10
	v_mad_u64_u32 v[8:9], s[16:17], v10, s13, v[8:9]
	v_lshl_add_u64 v[8:9], v[6:7], 1, v[8:9]
	v_add_co_u32_e32 v8, vcc, 0x15d00000, v8
	s_nop 1
	v_addc_co_u32_e32 v9, vcc, 0, v9, vcc
	global_load_ushort v6, v[8:9], off
	v_mov_b32_e32 v13, 0
	v_mov_b32_e32 v8, s20
	v_mov_b32_e32 v9, s21
	v_lshl_add_u64 v[8:9], v[12:13], 2, v[8:9]
	v_add_co_u32_e32 v8, vcc, 0x94ef000, v8
	s_nop 1
	v_addc_co_u32_e32 v9, vcc, 0, v9, vcc
	s_or_b64 exec, exec, s[8:9]
	v_mov_b32_e32 v195, 0
	v_mov_b32_e32 v2, s20
	v_mov_b32_e32 v3, s21
	v_lshl_add_u64 v[2:3], v[194:195], 2, v[2:3]
	v_add_co_u32_e32 v2, vcc, 0x94ef000, v2
	s_nop 1
	v_addc_co_u32_e32 v3, vcc, 0, v3, vcc
	s_waitcnt vmcnt(0)
	v_lshlrev_b32_e32 v0, 16, v0
	global_store_dword v[2:3], v0, off
	v_cmp_ge_i32_e32 vcc, s15, v12
	s_and_saveexec_b64 s[8:9], vcc
	v_lshlrev_b32_e32 v6, 16, v6
	global_store_dword v[8:9], v6, off
	s_or_b64 exec, exec, s[8:9]
	s_branch .LBB0_848
